# PA phase stagger: odd workgroups of each XCD start PA 3.4us late (G=2) to de-burst store epilogues
# baseline (speedup 1.0000x reference)
;     __device__ bool next(int i, Unit& u) const {
;         const long L = (long)i * G + c; if (L >= nwg) return false;
;         int wgid = (int)L; { const int q = nwg / NXCD, r = nwg % NXCD, xcd = wgid % NXCD, off = wgid / NXCD; wgid = (xcd < r ? xcd * (q + 1) : r * (q + 1) + (xcd - r) * q) + off; }
;         const int nig = WGM * nN, gid = wgid / nig, fm = gid * WGM, gsz = (nM - fm) < WGM ? (nM - fm) : WGM;
;         u.pm = fm + ((wgid % nig) % gsz); u.pn = (wgid % nig) / gsz; return true;
;     }
; __global__ void __launch_bounds__(512, 2) fwd_kernel(Args a) {
;     ...
;     if (IN(1)) {
;         SchedA S; S.init(T, NIN, gridDim.x, blockIdx.x); S.XB = (const char*)(ws + WS_XB); S.W = (const char*)(ws + WS_WIN);
;         EpiA E; E.ws = ws; E.GA = (bf16_t*)a.out;
;         E.qn_a = a.in[4]; E.kn_a = a.in[5]; E.qn_b = a.in[7]; E.kn_b = a.in[8];
;         pg8::gemm_phase<EpiA, SchedA>(lds, S, E);
.LBB0_160:
	s_cmp_lt_i32 s66, 2
	s_cselect_b64 s[4:5], -1, 0
	s_and_b64 s[6:7], s[4:5], s[0:1]
	s_andn2_b64 vcc, exec, s[6:7]
	s_cbranch_vccnz .LBB0_212
	s_and_b32 s100, s2, 7
	s_lshl_b32 s100, s100, 7
	s_add_u32 s100, s100, s92
	s_addc_u32 s101, s93, 0
	s_add_u32 s100, s100, 0x3c00
	s_addc_u32 s101, s101, 0
	v_mov_b32_e32 v254, 0
	global_load_dword v255, v254, s[100:101] sc1
	s_waitcnt vmcnt(0)
	v_readfirstlane_b32 s32, v255
	s_nop 0
	s_bcnt1_i32_b32 s32, s32
	s_mov_b32 s99, -1
	s_lshr_b32 s100, s2, 3
	s_and_b32 s100, s100, 1
	s_mul_i32 s100, s100, 1
	s_cmp_eq_u32 s100, 0
	s_cbranch_scc1 .Lpastg_done
.Lpastg_loop:
	s_sleep 127
	s_add_i32 s100, s100, -1
	s_cmp_lg_u32 s100, 0
	s_cbranch_scc1 .Lpastg_loop
.Lpastg_done:
	s_cmpk_lt_i32 s2, 0xfc0
	s_cselect_b64 s[0:1], -1, 0
	s_cmpk_gt_i32 s2, 0xfbf
	v_readfirstlane_b32 s4, v190
	s_cbranch_scc1 .LBB0_163
	s_ashr_i32 s5, s2, 31
	s_lshr_b32 s5, s5, 29
	s_add_i32 s5, s2, s5
	s_ashr_i32 s8, s5, 3
	s_and_b32 s5, s5, -8
	s_sub_i32 s5, s2, s5
	s_cmp_lt_i32 s5, 0
	s_movk_i32 s9, 0x1f9
	s_cselect_b32 s9, s9, 0x1f8
	s_mul_i32 s5, s5, s9
	s_add_i32 s5, s5, s8
	s_mul_hi_i32 s8, s5, 0x30c30c31
	s_lshr_b32 s9, s8, 31
	s_ashr_i32 s8, s8, 4
	s_add_i32 s8, s8, s9
	s_lshl_b32 s9, s8, 2
	s_mulk_i32 s8, 0x54
	s_sub_i32 s5, s5, s8
	s_bfe_i32 s8, s5, 0x80000
	s_bfe_u32 s8, s8, 0x2000d
	s_add_i32 s8, s5, s8
	s_bfe_i32 s10, s8, 0x80000
	s_and_b32 s8, s8, 0xfc
	s_sub_i32 s5, s5, s8
	s_sext_i32_i16 s10, s10
	s_sext_i32_i8 s5, s5
	s_add_i32 s8, s9, s5
	s_ashr_i32 s38, s10, 2
	s_mul_i32 s100, s8, 0xaab
	s_lshr_b32 s100, s100, 16
	s_mul_i32 s101, s100, 24
	s_sub_i32 s101, s8, s101
	s_lshl_b32 s101, s101, 3
	s_or_b32 s8, s101, s100
